# phase-4 opening qhn/khn max loop hoisted in front of the P3->P4 grid barrier (reads only kernel inputs)
# speedup vs baseline: 1.0240x; 1.0041x over previous
; DI unsigned xb_add(unsigned* p, unsigned v) { return __hip_atomic_fetch_add(p, v, __ATOMIC_RELAXED, __HIP_MEMORY_SCOPE_AGENT); }
; DI void xcd_barrier(const XcdBarrier& b) {
;   asm volatile("s_waitcnt vmcnt(0)" ::: "memory");
;   __syncthreads();
;   if (threadIdx.x == 0) {
;     unsigned* bar = b.bar;
;     __builtin_amdgcn_s_waitcnt(0);
;     const unsigned nloc = b.st[0], nx = b.st[1];
;     const unsigned old = xb_add(&bar[XB_XSUB(b.x)], 1u);
;     const unsigned gen = old / nloc;
;     if (old + 1u == (gen + 1u) * nloc) {
; DI void phase4(const Params& p, char* smem, const Sched sc) {
;     ...
;   for (int i = 0; i < 96; ++i) { gq = fmaxf(gq, fabsf(p.qhn[i])); gk = fmaxf(gk, fabsf(p.khn[i])); }
.LBB0_380:
	s_load_dwordx4 s[8:11], s[68:69], 0x58
	s_mov_b64 s[0:1], 0
	v_mov_b32_e32 v0, 0
	v_mov_b32_e32 v1, 0
	v_mov_b32_e32 v2, 0
	s_waitcnt lgkmcnt(0)
.LBB0_418:
	s_add_u32 s2, s8, s0
	s_addc_u32 s3, s9, s1
	global_load_dwordx4 v[4:7], v0, s[2:3] offset:32
	global_load_dwordx4 v[8:11], v0, s[2:3] offset:16
	global_load_dwordx4 v[12:15], v0, s[2:3]
	s_add_u32 s2, s10, s0
	s_addc_u32 s3, s11, s1
	global_load_dwordx4 v[16:19], v0, s[2:3]
	global_load_dwordx4 v[20:23], v0, s[2:3] offset:16
	global_load_dwordx4 v[24:27], v0, s[2:3] offset:32
	s_add_u32 s0, s0, 48
	s_addc_u32 s1, s1, 0
	s_cmpk_eq_i32 s0, 0x180
	s_waitcnt vmcnt(3)
	v_max3_f32 v1, v1, |v12|, |v13|
	s_waitcnt vmcnt(2)
	v_max3_f32 v2, v2, |v16|, |v17|
	v_max3_f32 v1, v1, |v14|, |v15|
	v_max3_f32 v2, v2, |v18|, |v19|
	v_max3_f32 v1, v1, |v8|, |v9|
	s_waitcnt vmcnt(1)
	v_max3_f32 v2, v2, |v20|, |v21|
	v_max3_f32 v1, v1, |v10|, |v11|
	v_max3_f32 v2, v2, |v22|, |v23|
	v_max3_f32 v1, v1, |v4|, |v5|
	s_waitcnt vmcnt(0)
	v_max3_f32 v2, v2, |v24|, |v25|
	v_max3_f32 v1, v1, |v6|, |v7|
	v_max3_f32 v2, v2, |v26|, |v27|
	s_cbranch_scc0 .LBB0_418
	v_mov_b32_e32 v215, v1
	v_mov_b32_e32 v216, v2
	s_waitcnt vmcnt(0)
	s_barrier
	s_and_saveexec_b64 s[0:1], s[72:73]
	s_cbranch_execz .LBB0_417
	v_mov_b32_e32 v0, 0x12400
	s_waitcnt vmcnt(0) expcnt(0) lgkmcnt(0)
	ds_read_b32 v2, v0
	v_mov_b32_e32 v0, 0x12404
	ds_read_b32 v0, v0
	s_mov_b64 s[4:5], exec
	v_readlane_b32 s2, v255, 4
	s_lshl_b32 s2, s2, 8
	v_mbcnt_lo_u32_b32 v1, s4, 0
	s_add_u32 s2, s70, s2
	v_mbcnt_hi_u32_b32 v1, s5, v1
	s_addc_u32 s3, s71, 0
	v_cmp_eq_u32_e32 vcc, 0, v1
	s_and_saveexec_b64 s[6:7], vcc
	s_cbranch_execz .LBB0_383
	s_bcnt1_i32_b64 s4, s[4:5]
	v_mov_b32_e32 v3, 0x1000
	v_mov_b32_e32 v4, s4
	global_atomic_add v3, v3, v4, s[2:3] offset:1024 sc0

; template <int DQK, bool SB, bool SMAX>
; DI void attn_item(const Params& p, char* smem, int bh, int qb, float Mb) {
;     ...
;   for (int s = 0; s < 2; ++s)
; #pragma unroll
;     for (int j = 0; j < 8; ++j) tri[s][j] = ((16 * s + 8 * (j >> 2) + 4 * h + (j & 3)) >= r) ? (short)0x3F80 : (short)0;
; #pragma unroll
;   for (int j = 0; j < 8; ++j) ones[j] = (short)0x3F80;
;   const int nt = 2 * (qb + 1);
;   f32x16 O[2];
; #pragma unroll
;   for (int db = 0; db < 2; ++db)
; #pragma unroll
;     for (int i = 0; i < 16; ++i) O[db][i] = 0.f;
;   float m = -__builtin_huge_valf(), lsum = 0.f, carry = 0.f;
;   f32x16 negM;
; #pragma unroll
;   for (int i = 0; i < 16; ++i) negM[i] = -Mb;
;   u32x4 kreg[1][KPT], vreg[1][2];
;     ...
;   const int blk = (lane >> 4) & 1, tq = (lane & 15) >> 2, tp = lane & 3;
;   const int voff = (4 * h + tq) * VSTR + 16 * blk + 4 * tp;
; DI void phase4(const Params& p, char* smem, const Sched sc) {
;     ...
;   for (int i = 0; i < 96; ++i) { gq = fmaxf(gq, fabsf(p.qhn[i])); gk = fmaxf(gk, fabsf(p.khn[i])); }
;   const float Mb = LOG2E * 9.797958971132712f * gq * gk * 1.02f;
;   const bool smax = Mb < 56.f;
.LBB0_417:
	s_or_b64 exec, exec, s[0:1]
	s_waitcnt lgkmcnt(0)
	s_barrier
	v_mov_b32_e32 v1, v215
	v_mov_b32_e32 v2, v216
	v_readlane_b32 s0, v255, 5
	v_readlane_b32 s1, v255, 6
	s_and_b64 vcc, exec, s[0:1]
	s_cbranch_vccnz .LBB0_487
	v_lshlrev_b32_e32 v197, 2, v171
	v_mul_f32_e32 v0, 0x41622ae0, v1
	v_mov_b32_e32 v1, 0x3f80
	v_cmp_lt_u32_e32 vcc, v197, v226
	v_or_b32_e32 v4, 1, v197
	v_mul_f32_e32 v0, v2, v0
	v_cndmask_b32_e64 v2, v1, 0, vcc
	v_or_b32_e32 v3, 2, v197
	v_cmp_lt_u32_e32 vcc, v4, v226
	v_or_b32_e32 v6, 3, v197
	v_or_b32_e32 v5, 8, v197
	v_cndmask_b32_e64 v4, v1, 0, vcc
	v_cmp_lt_u32_e32 vcc, v3, v226
	v_or_b32_e32 v7, 10, v197
	v_or_b32_e32 v8, 9, v197
	v_cndmask_b32_e64 v3, v1, 0, vcc
	v_cmp_lt_u32_e32 vcc, v6, v226
	v_or_b32_e32 v9, 11, v197
	v_or_b32_e32 v10, 16, v197
	v_cndmask_b32_e64 v6, v1, 0, vcc
	v_cmp_lt_u32_e32 vcc, v5, v226
	v_or_b32_e32 v12, 17, v197
	v_or_b32_e32 v11, 18, v197
	v_cndmask_b32_e64 v5, v1, 0, vcc
	v_cmp_lt_u32_e32 vcc, v7, v226
	v_or_b32_e32 v14, 19, v197
	v_or_b32_e32 v13, 24, v197
	v_cndmask_b32_e64 v7, v1, 0, vcc
	v_cmp_lt_u32_e32 vcc, v8, v226
	v_or_b32_e32 v15, 26, v197
	v_writelane_b32 v255, s75, 7
	v_cndmask_b32_e64 v8, v1, 0, vcc
	v_cmp_lt_u32_e32 vcc, v9, v226
	v_mul_f32_e32 v0, 0x3f828f5c, v0
	s_mov_b32 s0, 0x42600000
	v_cndmask_b32_e64 v9, v1, 0, vcc
	v_cmp_lt_u32_e32 vcc, v10, v226
	v_or_b32_e32 v16, 25, v197
	v_writelane_b32 v255, s74, 8
	v_cndmask_b32_e64 v10, v1, 0, vcc
	v_cmp_lt_u32_e32 vcc, v12, v226
	v_cmp_ngt_f32_e64 s[0:1], s0, v0
	v_or_b32_e32 v17, 27, v197
	v_cndmask_b32_e64 v12, v1, 0, vcc
	v_cmp_lt_u32_e32 vcc, v11, v226
	v_writelane_b32 v255, s0, 9
	v_and_b32_e32 v18, 16, v241
	v_cndmask_b32_e64 v11, v1, 0, vcc
	v_cmp_lt_u32_e32 vcc, v14, v226
	v_writelane_b32 v255, s1, 10
	s_mov_b32 s0, 0x5040100
	v_cndmask_b32_e64 v14, v1, 0, vcc
	v_cmp_lt_u32_e32 vcc, v13, v226
	v_perm_b32 v96, v4, v2, s0
	v_add_u32_e32 v21, 0x100, v241
	v_cndmask_b32_e64 v13, v1, 0, vcc
	v_cmp_lt_u32_e32 vcc, v15, v226
	v_and_b32_e32 v23, 24, v176
	v_lshl_or_b32 v198, v18, 1, v23
	v_cndmask_b32_e64 v15, v1, 0, vcc
	v_cmp_lt_u32_e32 vcc, v16, v226
	v_lshrrev_b32_e32 v22, 3, v21
	s_load_dwordx8 s[80:87], s[68:69], 0xf8
	v_cndmask_b32_e64 v16, v1, 0, vcc
	v_cmp_lt_u32_e32 vcc, v17, v226
	v_perm_b32 v102, v16, v13, s0
	v_writelane_b32 v255, s68, 11
	v_cndmask_b32_e64 v1, v1, 0, vcc
	v_perm_b32 v103, v1, v15, s0
	v_mul_u32_u24_e32 v1, 0xaaab, v241
	v_lshrrev_b32_e32 v1, 19, v1
	v_mul_lo_u16_e32 v2, 12, v1
	v_mul_u32_u24_e32 v16, 0xd0, v1
	v_sub_u16_e32 v1, v241, v2
	v_lshlrev_b32_e32 v18, 4, v1
	v_mul_u32_u24_e32 v1, 0xaaab, v21
	v_lshrrev_b32_e32 v1, 19, v1
	v_mul_lo_u16_e32 v2, 12, v1
	v_mul_u32_u24_e32 v23, 0xd0, v1
	v_sub_u16_e32 v1, v21, v2
	v_lshlrev_b32_e32 v21, 4, v1
	v_add_u16_e32 v1, 0x200, v241
	v_mul_u32_u24_e32 v2, 0xaaab, v1
	v_lshrrev_b32_e32 v2, 19, v2
	s_load_dwordx8 s[88:95], s[68:69], 0xc0
	v_bfe_u32 v17, v241, 2, 2
	v_perm_b32 v97, v6, v3, s0
	v_mul_lo_u16_e32 v3, 12, v2
	v_mov_b32_e32 v177, 0
	v_or_b32_e32 v17, v197, v17
	v_sub_u16_e32 v1, v1, v3
	v_and_b32_e32 v19, 0x70, v214
	v_mul_u32_u24_e32 v20, 0x90, v232
	v_mul_u32_u24_e32 v22, 0x90, v22
	v_cmp_eq_u32_e64 s[8:9], 0, v179
	v_mul_u32_u24_e32 v200, 0x90, v17
	v_mul_u32_u24_e32 v17, 0x90, v226
	v_perm_b32 v98, v8, v5, s0
	v_perm_b32 v99, v9, v7, s0
	v_perm_b32 v101, v14, v11, s0
	v_perm_b32 v100, v12, v10, s0
	v_mul_u32_u24_e32 v24, 0xd0, v2
	v_lshlrev_b32_e32 v25, 4, v1
	v_xor_b32_e32 v0, 0x80000000, v0
	v_writelane_b32 v255, s69, 12
	v_mov_b32_e32 v179, v177
	s_mov_b32 s0, s76
	v_lshlrev_b32_e32 v196, 5, v254
	s_mov_b32 s5, 0
	v_lshlrev_b32_e32 v199, 2, v254
	v_cmp_eq_u32_e64 s[10:11], 0, v181
	v_and_b32_e32 v201, 0x1e0, v213
	v_mul_u32_u24_e32 v202, 0xd0, v226
	v_mov_b32_e32 v1, v0
	v_mov_b32_e32 v2, v0
	v_mov_b32_e32 v3, v0
	v_mov_b32_e32 v4, v0
	v_mov_b32_e32 v5, v0
	v_mov_b32_e32 v6, v0
	v_mov_b32_e32 v7, v0
	v_mov_b32_e32 v8, v0
	v_mov_b32_e32 v9, v0
	v_mov_b32_e32 v10, v0
	v_mov_b32_e32 v11, v0
	v_mov_b32_e32 v12, v0
	v_mov_b32_e32 v13, v0
	v_mov_b32_e32 v14, v0
	v_mov_b32_e32 v15, v0
	s_waitcnt lgkmcnt(0)
	v_lshl_add_u64 v[172:173], s[80:81], 0, v[178:179]
	v_mov_b32_e32 v179, 0x123f0
	s_movk_i32 s6, 0x2000
	v_lshlrev_b64 v[174:175], 1, v[176:177]
	s_movk_i32 s7, 0x1000
	v_add_u32_e32 v203, v19, v20
	v_add_u32_e32 v204, v19, v22
	s_mov_b32 s96, 0x3f803f80
	s_mov_b32 s76, 0xc2800000
	v_lshlrev_b32_e32 v180, 1, v180
	v_add_u32_e32 v205, v178, v17
	v_add_u32_e32 v206, v16, v18
	v_add_u32_e32 v207, v23, v21
	v_add_u32_e32 v208, v24, v25
	v_mov_b32_e32 v209, 0xc0
	v_mov_b32_e32 v210, 0xff800000
	v_writelane_b32 v255, s0, 13
	s_mov_b32 s2, s0
	s_branch .LBB0_422
